# X47: Mamba-2 inter-chunk scan loop - removed a false-dependency vmcnt wait (pair-high halves of broadcast operands are next-batch load destinations) and the store-ack wait at the loop top, so the pref
# baseline (speedup 1.0000x reference)
; __device__ __forceinline__ void sd_p2_item4(unsigned char* ws, int item, int t) {
;     const bf16* STATES = (const bf16*)(ws + WS_SDST); const float* CDEC = (const float*)(ws + WS_CDEC); bf16* PREV = (bf16*)(ws + WS_SDPV);
;     const int bh = item >> 3, b = bh >> 3, h = bh & 7, pp = (item & 7) * 8 + (t >> 5), n = 4 * (t & 31);
;     f32x4 s = {0.f, 0.f, 0.f, 0.f}; constexpr int U = 8; v2u ru[U]; float rd[U];
;     ...
; #pragma unroll
;     for (int i = 0; i < U; ++i) { ru[i] = *(const v2u*)(STATES + SD_IDX4(i)); rd[i] = CDEC[(size_t)(b * 256 + i) * 8 + h]; }
.LBB0_923:
	s_cmp_gt_i32 s51, 3
	s_mov_b64 s[22:23], -1
	s_cbranch_scc0 .LBB0_938
	s_cmpk_gt_u32 s51, 0x83
	s_cbranch_scc0 .LBB0_932
	s_lshr_b32 s5, s50, 6
	s_lshr_b32 s4, s50, 3
	s_lshl_b32 s6, s5, 11
	s_add_i32 s4, s4, s6
	s_add_i32 s33, s4, 64
	s_bfe_u32 s4, s50, 0x30003
	s_or_b32 s6, s6, s4
	s_lshl_b32 s5, s5, 24
	s_lshl_b32 s4, s4, 13
	s_or_b32 s4, s5, s4
	s_add_i32 s5, s51, 0xffffff7c
	s_lshl_b32 s7, s5, 3
	s_and_b32 s7, s7, 56
	s_or_b32 s22, s6, 64
	s_bfe_u32 s6, s5, 0x30003
	s_lshl_b32 s5, s5, 5
	v_add_lshl_u32 v6, s7, v3, 7
	s_and_b32 s5, s5, 0xfffff800
	v_ashrrev_i32_e32 v7, 31, v6
	s_or_b32 s24, s5, s6
	v_lshlrev_b64 v[22:23], 1, v[6:7]
	v_lshl_add_u64 v[6:7], v[70:71], 0, v[22:23]
	s_lshl_b64 s[34:35], s[24:25], 14
	v_lshl_add_u64 v[8:9], v[6:7], 0, s[34:35]
	s_lshl_b64 s[34:35], s[24:25], 2
	s_add_u32 s34, s2, s34
	s_addc_u32 s35, s3, s35
	global_load_dwordx2 v[32:33], v[8:9], off
	global_load_dword v38, v5, s[34:35]
	s_or_b32 s34, s24, 8
	s_mov_b32 s35, s25
	s_lshl_b64 s[42:43], s[34:35], 14
	s_lshl_b64 s[34:35], s[34:35], 2
	s_add_u32 s34, s2, s34
	v_lshl_add_u64 v[8:9], v[6:7], 0, s[42:43]
	s_addc_u32 s35, s3, s35
	global_load_dwordx2 v[24:25], v[8:9], off
	global_load_dword v36, v5, s[34:35]
	s_or_b32 s34, s24, 16
	s_mov_b32 s35, s25
	s_lshl_b64 s[42:43], s[34:35], 14
	s_lshl_b64 s[34:35], s[34:35], 2
	s_add_u32 s34, s2, s34
	v_lshl_add_u64 v[8:9], v[6:7], 0, s[42:43]
	s_addc_u32 s35, s3, s35
	global_load_dwordx2 v[18:19], v[8:9], off
	global_load_dword v30, v5, s[34:35]
	s_or_b32 s34, s24, 24
	s_mov_b32 s35, s25
	s_lshl_b64 s[42:43], s[34:35], 14
	s_lshl_b64 s[34:35], s[34:35], 2
	s_add_u32 s34, s2, s34
	v_lshl_add_u64 v[8:9], v[6:7], 0, s[42:43]
	s_addc_u32 s35, s3, s35
	global_load_dwordx2 v[26:27], v[8:9], off
	global_load_dword v34, v5, s[34:35]
	s_or_b32 s34, s24, 32
	s_mov_b32 s35, s25
	s_lshl_b64 s[42:43], s[34:35], 14
	s_lshl_b64 s[34:35], s[34:35], 2
	s_add_u32 s34, s2, s34
	v_lshl_add_u64 v[8:9], v[6:7], 0, s[42:43]
	s_addc_u32 s35, s3, s35
	global_load_dwordx2 v[16:17], v[8:9], off
	global_load_dword v28, v5, s[34:35]
	s_or_b32 s34, s24, 40
	s_mov_b32 s35, s25
	s_lshl_b64 s[42:43], s[34:35], 14
	s_lshl_b64 s[34:35], s[34:35], 2
	s_add_u32 s34, s2, s34
	v_lshl_add_u64 v[8:9], v[6:7], 0, s[42:43]
	s_addc_u32 s35, s3, s35
	global_load_dwordx2 v[10:11], v[8:9], off
	global_load_dword v20, v5, s[34:35]
	s_or_b32 s34, s24, 48
	s_mov_b32 s35, s25
	s_lshl_b64 s[42:43], s[34:35], 14
	s_lshl_b64 s[34:35], s[34:35], 2
	s_add_u32 s34, s2, s34
	v_lshl_add_u64 v[8:9], v[6:7], 0, s[42:43]
	s_addc_u32 s35, s3, s35
	s_or_b32 s24, s24, 56
	global_load_dwordx2 v[8:9], v[8:9], off
	v_mov_b32_e32 v46, 0
	global_load_dword v14, v5, s[34:35]
	s_lshl_b64 s[34:35], s[24:25], 14
	v_lshl_add_u64 v[12:13], v[6:7], 0, s[34:35]
	s_lshl_b64 s[34:35], s[24:25], 2
	s_add_u32 s34, s2, s34
	s_addc_u32 s35, s3, s35
	global_load_dwordx2 v[12:13], v[12:13], off
	v_lshl_add_u64 v[22:23], v[72:73], 0, v[22:23]
	global_load_dword v40, v5, s[34:35]
	s_mov_b32 s52, 0
	s_mov_b32 s24, s4
	v_mov_b32_e32 v47, v46
	v_mov_b32_e32 v50, v46
	v_mov_b32_e32 v51, v46
	s_waitcnt vmcnt(0)
	s_branch .LBB0_927
; __device__ __forceinline__ unsigned pk2(float lo, float hi) { const f32x2_t v = {lo, hi}; return __builtin_bit_cast(unsigned, __builtin_convertvector(v, bf16x2_t)); }
; __device__ __forceinline__ void sd_p2_item4(unsigned char* ws, int item, int t) {
;     ...
;     for (int c0 = 0; c0 < 256; c0 += U) {
;         v2u cu[U]; float cd[U];
; #pragma unroll
;         for (int i = 0; i < U; ++i) { cu[i] = ru[i]; cd[i] = rd[i]; }
;         if (c0 + U < 256) {
; #pragma unroll
;             for (int i = 0; i < U; ++i) { ru[i] = *(const v2u*)(STATES + SD_IDX4(c0 + U + i)); rd[i] = CDEC[(size_t)(b * 256 + c0 + U + i) * 8 + h]; } }
; #pragma unroll
;         for (int i = 0; i < U; ++i) { *(v2u*)(PREV + SD_IDX4(c0 + i)) = (v2u){pk2(s.x, s.y), pk2(s.z, s.w)};
;             s = s * cd[i] + (f32x4){bflo(cu[i].x), bfhi(cu[i].x), bflo(cu[i].y), bfhi(cu[i].y)}; }
;     }
.LBB0_926:
	v_cvt_pk_bf16_f32 v62, v46, v47
	v_cvt_pk_bf16_f32 v63, v50, v51
	v_lshl_add_u64 v[64:65], s[24:25], 1, v[22:23]
	global_store_dwordx2 v[64:65], v[62:63], off
	v_lshlrev_b32_e32 v62, 16, v32
	v_and_b32_e32 v63, 0xffff0000, v32
	v_lshlrev_b32_e32 v32, 16, v33
	v_and_b32_e32 v33, 0xffff0000, v33
	s_mov_b32 s4, 0x20000
	v_pk_fma_f32 v[32:33], v[50:51], v[38:39], v[32:33] op_sel_hi:[1,0,1]
	v_pk_fma_f32 v[46:47], v[46:47], v[38:39], v[62:63] op_sel_hi:[1,0,1]
	v_add_co_u32_e32 v62, vcc, s4, v64
	v_cvt_pk_bf16_f32 v50, v46, v47
	v_cvt_pk_bf16_f32 v51, v32, v33
	v_addc_co_u32_e32 v63, vcc, 0, v65, vcc
	global_store_dwordx2 v[62:63], v[50:51], off
	v_lshlrev_b32_e32 v50, 16, v24
	v_and_b32_e32 v51, 0xffff0000, v24
	v_lshlrev_b32_e32 v24, 16, v25
	v_and_b32_e32 v25, 0xffff0000, v25
	s_mov_b32 s4, 0x40000
	v_pk_fma_f32 v[24:25], v[36:37], v[32:33], v[24:25] op_sel_hi:[0,1,1]
	v_pk_fma_f32 v[32:33], v[36:37], v[46:47], v[50:51] op_sel_hi:[0,1,1]
	v_add_co_u32_e32 v50, vcc, s4, v64
	v_cvt_pk_bf16_f32 v46, v32, v33
	v_cvt_pk_bf16_f32 v47, v24, v25
	v_addc_co_u32_e32 v51, vcc, 0, v65, vcc
	global_store_dwordx2 v[50:51], v[46:47], off
	v_lshlrev_b32_e32 v46, 16, v18
	v_and_b32_e32 v47, 0xffff0000, v18
	v_lshlrev_b32_e32 v18, 16, v19
	v_and_b32_e32 v19, 0xffff0000, v19
	v_pk_fma_f32 v[18:19], v[30:31], v[24:25], v[18:19] op_sel_hi:[0,1,1]
	v_pk_fma_f32 v[24:25], v[30:31], v[32:33], v[46:47] op_sel_hi:[0,1,1]
	v_add_co_u32_e32 v46, vcc, s69, v64
	v_cvt_pk_bf16_f32 v32, v24, v25
	v_cvt_pk_bf16_f32 v33, v18, v19
	v_addc_co_u32_e32 v47, vcc, 0, v65, vcc
	global_store_dwordx2 v[46:47], v[32:33], off
	v_lshlrev_b32_e32 v32, 16, v26
	v_and_b32_e32 v33, 0xffff0000, v26
	v_lshlrev_b32_e32 v26, 16, v27
	v_and_b32_e32 v27, 0xffff0000, v27
	s_mov_b32 s4, 0x80000
	v_pk_fma_f32 v[18:19], v[34:35], v[18:19], v[26:27] op_sel_hi:[0,1,1]
	v_pk_fma_f32 v[24:25], v[34:35], v[24:25], v[32:33] op_sel_hi:[0,1,1]
	v_add_co_u32_e32 v32, vcc, s4, v64
	v_cvt_pk_bf16_f32 v26, v24, v25
	v_cvt_pk_bf16_f32 v27, v18, v19
	v_addc_co_u32_e32 v33, vcc, 0, v65, vcc
	global_store_dwordx2 v[32:33], v[26:27], off
	v_lshlrev_b32_e32 v26, 16, v16
	v_and_b32_e32 v27, 0xffff0000, v16
	v_lshlrev_b32_e32 v16, 16, v17
	v_and_b32_e32 v17, 0xffff0000, v17
	s_mov_b32 s4, 0xa0000
	v_pk_fma_f32 v[16:17], v[28:29], v[18:19], v[16:17] op_sel_hi:[0,1,1]
	v_pk_fma_f32 v[18:19], v[28:29], v[24:25], v[26:27] op_sel_hi:[0,1,1]
	v_add_co_u32_e32 v26, vcc, s4, v64
	v_cvt_pk_bf16_f32 v24, v18, v19
	v_cvt_pk_bf16_f32 v25, v16, v17
	v_addc_co_u32_e32 v27, vcc, 0, v65, vcc
	global_store_dwordx2 v[26:27], v[24:25], off
	v_lshlrev_b32_e32 v24, 16, v10
	v_and_b32_e32 v25, 0xffff0000, v10
	v_lshlrev_b32_e32 v10, 16, v11
	v_and_b32_e32 v11, 0xffff0000, v11
	s_mov_b32 s4, 0xc0000
	v_pk_fma_f32 v[10:11], v[20:21], v[16:17], v[10:11] op_sel_hi:[0,1,1]
	v_pk_fma_f32 v[16:17], v[20:21], v[18:19], v[24:25] op_sel_hi:[0,1,1]
	v_add_co_u32_e32 v24, vcc, s4, v64
	v_cvt_pk_bf16_f32 v18, v16, v17
	v_cvt_pk_bf16_f32 v19, v10, v11
	v_addc_co_u32_e32 v25, vcc, 0, v65, vcc
	global_store_dwordx2 v[24:25], v[18:19], off
	v_lshlrev_b32_e32 v18, 16, v8
	v_and_b32_e32 v19, 0xffff0000, v8
	v_lshlrev_b32_e32 v8, 16, v9
	v_and_b32_e32 v9, 0xffff0000, v9
	s_mov_b32 s4, 0xe0000
	v_pk_fma_f32 v[8:9], v[14:15], v[10:11], v[8:9] op_sel_hi:[0,1,1]
	v_pk_fma_f32 v[10:11], v[14:15], v[16:17], v[18:19] op_sel_hi:[0,1,1]
	v_add_co_u32_e32 v18, vcc, s4, v64
	v_cvt_pk_bf16_f32 v16, v10, v11
	v_cvt_pk_bf16_f32 v17, v8, v9
	v_addc_co_u32_e32 v19, vcc, 0, v65, vcc
	global_store_dwordx2 v[18:19], v[16:17], off
	v_lshlrev_b32_e32 v16, 16, v12
	v_and_b32_e32 v17, 0xffff0000, v12
	v_lshlrev_b32_e32 v12, 16, v13
	v_and_b32_e32 v13, 0xffff0000, v13
	s_add_i32 s52, s52, 8
	s_waitcnt vmcnt(9)
	v_pk_fma_f32 v[50:51], v[40:41], v[8:9], v[12:13] op_sel_hi:[0,1,1]
	v_pk_fma_f32 v[46:47], v[40:41], v[10:11], v[16:17] op_sel_hi:[0,1,1]
	s_add_i32 s33, s33, 64
	s_add_i32 s22, s22, 64
	s_andn2_b64 vcc, exec, s[42:43]
	s_mov_b32 s24, s44
	s_waitcnt vmcnt(8)
	v_mov_b64_e32 v[12:13], v[60:61]
	v_mov_b64_e32 v[8:9], v[58:59]
	v_mov_b64_e32 v[10:11], v[56:57]
	v_mov_b64_e32 v[16:17], v[54:55]
	v_mov_b64_e32 v[26:27], v[52:53]
	v_mov_b64_e32 v[18:19], v[48:49]
	v_mov_b64_e32 v[24:25], v[44:45]
	v_mov_b64_e32 v[32:33], v[42:43]
	v_mov_b32_e32 v40, v41
	v_mov_b32_e32 v14, v39
	v_mov_b32_e32 v20, v37
	v_mov_b32_e32 v28, v35
	v_mov_b32_e32 v34, v31
	v_mov_b32_e32 v30, v29
	v_mov_b32_e32 v36, v21
	v_mov_b32_e32 v38, v15
	s_cbranch_vccz .LBB0_931

; __device__ __forceinline__ void sd_p2_item4(unsigned char* ws, int item, int t) {
;     ...
;     for (int c0 = 0; c0 < 256; c0 += U) {
;         v2u cu[U]; float cd[U];
; #pragma unroll
;         for (int i = 0; i < U; ++i) { cu[i] = ru[i]; cd[i] = rd[i]; }
;         if (c0 + U < 256) {
; #pragma unroll
;             for (int i = 0; i < U; ++i) { ru[i] = *(const v2u*)(STATES + SD_IDX4(c0 + U + i)); rd[i] = CDEC[(size_t)(b * 256 + c0 + U + i) * 8 + h]; } }
.LBB0_929:
	s_andn2_b64 vcc, exec, s[46:47]
	s_waitcnt vmcnt(8)
	v_mov_b64_e32 v[60:61], v[12:13]
	v_mov_b64_e32 v[58:59], v[8:9]
	v_mov_b64_e32 v[56:57], v[10:11]
	v_mov_b64_e32 v[54:55], v[16:17]
	v_mov_b64_e32 v[52:53], v[26:27]
	v_mov_b64_e32 v[48:49], v[18:19]
	v_mov_b64_e32 v[44:45], v[24:25]
	v_mov_b64_e32 v[42:43], v[32:33]
	s_waitcnt vmcnt(8)
	v_mov_b32_e32 v41, v40
	v_mov_b32_e32 v39, v14
	v_mov_b32_e32 v37, v20
	v_mov_b32_e32 v35, v28
	v_mov_b32_e32 v31, v34
	v_mov_b32_e32 v29, v30
	v_mov_b32_e32 v21, v36
	v_mov_b32_e32 v15, v38
	s_cbranch_vccnz .LBB0_926
	s_mov_b32 s23, s25
	s_add_i32 s44, s24, 0x80000
	s_lshl_b64 s[34:35], s[22:23], 2
	s_add_u32 s46, s2, s34
	s_mov_b32 s45, s25
	s_addc_u32 s47, s3, s35
	s_or_b32 s34, s33, 8
	s_mov_b32 s35, s25
	v_lshl_add_u64 v[60:61], s[44:45], 1, v[6:7]
	s_lshl_b64 s[34:35], s[34:35], 2
	v_add_co_u32_e32 v44, vcc, 0x20000, v60
	s_add_u32 s34, s2, s34
	s_nop 0
	v_addc_co_u32_e32 v45, vcc, 0, v61, vcc
	s_addc_u32 s35, s3, s35
	s_mov_b32 s4, 0x40000
	global_load_dwordx2 v[42:43], v[60:61], off
	global_load_dword v15, v5, s[46:47]
	v_add_co_u32_e32 v48, vcc, s4, v60
	global_load_dwordx2 v[44:45], v[44:45], off
	s_nop 0
	v_addc_co_u32_e32 v49, vcc, 0, v61, vcc
	global_load_dword v21, v5, s[34:35]
	s_or_b32 s34, s33, 24
	s_mov_b32 s35, s25
	s_lshl_b64 s[34:35], s[34:35], 2
	v_add_co_u32_e32 v52, vcc, s69, v60
	s_add_u32 s34, s2, s34
	s_nop 0
	v_addc_co_u32_e32 v53, vcc, 0, v61, vcc
	s_addc_u32 s35, s3, s35
	s_mov_b32 s4, 0x80000
	global_load_dwordx2 v[48:49], v[48:49], off
	s_nop 0
	global_load_dword v29, v5, s[46:47] offset:64
	global_load_dword v31, v5, s[34:35]
	v_add_co_u32_e32 v54, vcc, s4, v60
	global_load_dwordx2 v[52:53], v[52:53], off
	s_or_b32 s34, s33, 40
	s_mov_b32 s35, s25
	v_addc_co_u32_e32 v55, vcc, 0, v61, vcc
	s_mov_b32 s4, 0xa0000
	s_lshl_b64 s[34:35], s[34:35], 2
	v_add_co_u32_e32 v56, vcc, s4, v60
	s_add_u32 s34, s2, s34
	s_nop 0
	v_addc_co_u32_e32 v57, vcc, 0, v61, vcc
	s_addc_u32 s35, s3, s35
	s_mov_b32 s4, 0xc0000
	global_load_dwordx2 v[54:55], v[54:55], off
	s_nop 0
	global_load_dword v35, v5, s[46:47] offset:128
	global_load_dword v37, v5, s[34:35]
	v_add_co_u32_e32 v58, vcc, s4, v60
	global_load_dwordx2 v[56:57], v[56:57], off
	s_or_b32 s34, s33, 56
	s_mov_b32 s35, s25
	v_addc_co_u32_e32 v59, vcc, 0, v61, vcc
	s_lshl_b64 s[34:35], s[34:35], 2
	v_add_co_u32_e32 v60, vcc, 0xe0000, v60
	s_add_u32 s34, s2, s34
	s_nop 0
	v_addc_co_u32_e32 v61, vcc, 0, v61, vcc
	s_addc_u32 s35, s3, s35
	global_load_dwordx2 v[58:59], v[58:59], off
	s_nop 0
	global_load_dword v39, v5, s[46:47] offset:192
	global_load_dword v41, v5, s[34:35]
	s_nop 0
	global_load_dwordx2 v[60:61], v[60:61], off
	s_branch .LBB0_926
